# prologue: the 160 workgroups without an adaLN unit pull the first 30 MB of x through the memory-side cache before the first barrier (cache warm-up for the norm phase)
# baseline (speedup 1.0000x reference)
.LBB0_97:
	s_cmp_lg_u32 s74, 0x100
	s_cbranch_scc1 .Lxp_done
	s_cmp_lt_u32 s93, 0x60
	s_cbranch_scc1 .Lxp_done
	s_load_dwordx2 s[28:29], s[82:83], 0x0
	v_mbcnt_lo_u32_b32 v196, -1, 0
	v_mbcnt_hi_u32_b32 v196, -1, v196
	v_add_u32_e32 v196, s3, v196
	v_lshlrev_b32_e32 v196, 4, v196
	s_add_i32 s0, s93, 0xffffffa0
	s_lshl_b32 s0, s0, 13
	v_add_u32_e32 v196, s0, v196
	s_mov_b32 s1, 0
	s_waitcnt lgkmcnt(0)
.Lxp_loop:
	global_load_dwordx4 v[198:201], v196, s[28:29]
	v_add_u32_e32 v196, 0x140000, v196
	s_add_i32 s1, s1, 1
	s_cmp_lt_u32 s1, 24
	s_cbranch_scc1 .Lxp_loop
